# grid barrier: L1 invalidate issued before the release spin instead of after it
# speedup vs baseline: 1.0060x; 1.0060x over previous
; __device__ __forceinline__ unsigned xb_ld(unsigned* p)              { return __hip_atomic_load(p, __ATOMIC_RELAXED, __HIP_MEMORY_SCOPE_AGENT); }
; __device__ __forceinline__ unsigned xb_add(unsigned* p, unsigned v) { return __hip_atomic_fetch_add(p, v, __ATOMIC_RELAXED, __HIP_MEMORY_SCOPE_AGENT); }
; #define XB_SPIN(cond, bar) do { unsigned _sp = 0; while (cond) { __builtin_amdgcn_s_sleep(1); \
;     if ((++_sp & 255u) == 0u) { if (xb_ld(&(bar)[XB_TMO])) break; if (_sp > XB_SPIN_CAP) { atomicAdd(&(bar)[XB_TMO], 1u); break; } } } } while (0)
; __device__ __forceinline__ void xcd_barrier(const XcdBarrier& b) {
;     ...
;         const unsigned old = xb_add(&bar[XB_XSUB(b.x)], 1u);
;         const unsigned gen = old / nloc;
;         if (old + 1u == (gen + 1u) * nloc) {
;             __builtin_amdgcn_fence(__ATOMIC_RELEASE, "agent");
;             asm volatile("s_waitcnt vmcnt(0)" ::: "memory");
;             const unsigned og = xb_add(&bar[XB_TOP], 1u);
;             const unsigned tg = og / nx;
;             if (og + 1u == (tg + 1u) * nx) xb_add(&bar[XB_TOPGEN], 1u);
;             else XB_SPIN(xb_ld(&bar[XB_TOPGEN]) == tg, bar);
;             __builtin_amdgcn_fence(__ATOMIC_ACQUIRE, "agent");
;             xb_add(&bar[XB_XGEN(b.x)], 1u);
;             asm volatile("s_waitcnt vmcnt(0)" ::: "memory");
;         } else {
;             XB_SPIN(xb_ld(&bar[XB_XGEN(b.x)]) == gen, bar);
;             __builtin_amdgcn_fence(__ATOMIC_ACQUIRE, "agent");
;             asm volatile("s_waitcnt vmcnt(0)" ::: "memory");
.LBB0_1038:
	s_or_b64 exec, exec, s[6:7]
	v_cvt_f32_u32_e32 v5, v3
	s_waitcnt vmcnt(0)
	v_readfirstlane_b32 s4, v4
	v_sub_u32_e32 v4, 0, v3
	v_rcp_iflag_f32_e32 v5, v5
	v_add_u32_e32 v6, s4, v0
	v_mul_f32_e32 v5, 0x4f7ffffe, v5
	v_cvt_u32_f32_e32 v5, v5
	v_mul_lo_u32 v0, v4, v5
	v_mul_hi_u32 v0, v5, v0
	v_add_u32_e32 v0, v5, v0
	v_mul_hi_u32 v0, v6, v0
	v_mul_lo_u32 v4, v0, v3
	v_sub_u32_e32 v4, v6, v4
	v_add_u32_e32 v5, 1, v0
	v_cmp_ge_u32_e32 vcc, v4, v3
	s_nop 1
	v_cndmask_b32_e32 v0, v0, v5, vcc
	v_sub_u32_e32 v5, v4, v3
	v_cndmask_b32_e32 v4, v4, v5, vcc
	v_add_u32_e32 v5, 1, v0
	v_cmp_ge_u32_e32 vcc, v4, v3
	v_add_u32_e32 v4, 1, v6
	s_nop 0
	v_cndmask_b32_e32 v0, v0, v5, vcc
	v_mul_lo_u32 v5, v3, v0
	v_add_u32_e32 v3, v5, v3
	v_cmp_ne_u32_e32 vcc, v4, v3
	s_and_saveexec_b64 s[4:5], vcc
	s_xor_b64 s[4:5], exec, s[4:5]
	s_cbranch_execz .LBB0_1052
	s_waitcnt lgkmcnt(0)
	v_mov_b32_e32 v2, 0x2000
	buffer_inv sc1
	global_load_dword v2, v2, s[2:3] offset:1024 sc1
	s_add_u32 s8, s2, 0x2400
	s_addc_u32 s9, s3, 0
	s_waitcnt vmcnt(0)
	v_cmp_eq_u32_e32 vcc, v2, v0
	s_and_saveexec_b64 s[6:7], vcc
	s_cbranch_execz .LBB0_1051
	s_mov_b32 s20, 1
	s_mov_b64 s[10:11], 0
	s_branch .LBB0_1042

; __device__ __forceinline__ unsigned xb_ld(unsigned* p)              { return __hip_atomic_load(p, __ATOMIC_RELAXED, __HIP_MEMORY_SCOPE_AGENT); }
; #define XB_SPIN(cond, bar) do { unsigned _sp = 0; while (cond) { __builtin_amdgcn_s_sleep(1); \
;     if ((++_sp & 255u) == 0u) { if (xb_ld(&(bar)[XB_TMO])) break; if (_sp > XB_SPIN_CAP) { atomicAdd(&(bar)[XB_TMO], 1u); break; } } } } while (0)
; __device__ __forceinline__ void xcd_barrier(const XcdBarrier& b) {
;     ...
;         } else {
;             XB_SPIN(xb_ld(&bar[XB_XGEN(b.x)]) == gen, bar);
;             __builtin_amdgcn_fence(__ATOMIC_ACQUIRE, "agent");
;             asm volatile("s_waitcnt vmcnt(0)" ::: "memory");
;         }
.LBB0_1051:
	s_or_b64 exec, exec, s[6:7]
	s_waitcnt vmcnt(0)
.LBB0_1052:
	s_andn2_saveexec_b64 s[4:5], s[4:5]
	s_cbranch_execnz .LBB0_1053
	s_getpc_b64 s[98:99]

; __device__ __forceinline__ unsigned xb_ld(unsigned* p)              { return __hip_atomic_load(p, __ATOMIC_RELAXED, __HIP_MEMORY_SCOPE_AGENT); }
; __device__ __forceinline__ unsigned xb_add(unsigned* p, unsigned v) { return __hip_atomic_fetch_add(p, v, __ATOMIC_RELAXED, __HIP_MEMORY_SCOPE_AGENT); }
; #define XB_SPIN(cond, bar) do { unsigned _sp = 0; while (cond) { __builtin_amdgcn_s_sleep(1); \
;     if ((++_sp & 255u) == 0u) { if (xb_ld(&(bar)[XB_TMO])) break; if (_sp > XB_SPIN_CAP) { atomicAdd(&(bar)[XB_TMO], 1u); break; } } } } while (0)
; __device__ __forceinline__ void xcd_barrier(const XcdBarrier& b) {
;     ...
;             const unsigned og = xb_add(&bar[XB_TOP], 1u);
;             const unsigned tg = og / nx;
;             if (og + 1u == (tg + 1u) * nx) xb_add(&bar[XB_TOPGEN], 1u);
;             else XB_SPIN(xb_ld(&bar[XB_TOPGEN]) == tg, bar);
.LBB0_1055:
	s_or_b64 exec, exec, s[6:7]
	s_waitcnt vmcnt(0)
	v_readfirstlane_b32 s4, v3
	v_sub_u32_e32 v4, 0, v2
	s_mov_b64 s[8:9], -1
	v_add_u32_e32 v3, s4, v0
	v_cvt_f32_u32_e32 v0, v2
	s_add_u32 s4, s90, 0x3500
	s_addc_u32 s5, s91, 0
	v_rcp_iflag_f32_e32 v0, v0
	s_nop 0
	v_mul_f32_e32 v0, 0x4f7ffffe, v0
	v_cvt_u32_f32_e32 v0, v0
	v_mul_lo_u32 v4, v4, v0
	v_mul_hi_u32 v4, v0, v4
	v_add_u32_e32 v0, v0, v4
	v_mul_hi_u32 v0, v3, v0
	v_mul_lo_u32 v4, v0, v2
	v_sub_u32_e32 v4, v3, v4
	v_cmp_ge_u32_e32 vcc, v4, v2
	v_add_u32_e32 v5, 1, v0
	v_add_u32_e32 v3, 1, v3
	v_cndmask_b32_e32 v0, v0, v5, vcc
	v_sub_u32_e32 v5, v4, v2
	v_cndmask_b32_e32 v4, v4, v5, vcc
	v_cmp_ge_u32_e32 vcc, v4, v2
	v_add_u32_e32 v4, 1, v0
	s_nop 0
	v_cndmask_b32_e32 v0, v0, v4, vcc
	v_mul_lo_u32 v4, v2, v0
	v_add_u32_e32 v2, v4, v2
	v_cmp_ne_u32_e32 vcc, v3, v2
	v_mov_b64_e32 v[2:3], s[4:5]
	s_and_saveexec_b64 s[6:7], vcc
	s_cbranch_execz .LBB0_1067
	buffer_inv sc1
	global_load_dword v2, v1, s[4:5] sc1
	s_mov_b64 s[12:13], 0
	s_waitcnt vmcnt(0)
	v_cmp_eq_u32_e32 vcc, v2, v0
	s_and_saveexec_b64 s[10:11], vcc
	s_cbranch_execz .LBB0_1066
	s_add_u32 s8, s90, 0x200
	s_addc_u32 s9, s91, 0
	s_mov_b32 s22, 1
	s_branch .LBB0_1059

; __device__ __forceinline__ unsigned xb_ld(unsigned* p)              { return __hip_atomic_load(p, __ATOMIC_RELAXED, __HIP_MEMORY_SCOPE_AGENT); }
; __device__ __forceinline__ unsigned xb_add(unsigned* p, unsigned v) { return __hip_atomic_fetch_add(p, v, __ATOMIC_RELAXED, __HIP_MEMORY_SCOPE_AGENT); }
; #define XB_SPIN(cond, bar) do { unsigned _sp = 0; while (cond) { __builtin_amdgcn_s_sleep(1); \
;     if ((++_sp & 255u) == 0u) { if (xb_ld(&(bar)[XB_TMO])) break; if (_sp > XB_SPIN_CAP) { atomicAdd(&(bar)[XB_TMO], 1u); break; } } } } while (0)
; __device__ __forceinline__ void xcd_barrier(const XcdBarrier& b) {
;     ...
;             if (og + 1u == (tg + 1u) * nx) xb_add(&bar[XB_TOPGEN], 1u);
;             else XB_SPIN(xb_ld(&bar[XB_TOPGEN]) == tg, bar);
;             __builtin_amdgcn_fence(__ATOMIC_ACQUIRE, "agent");
;             xb_add(&bar[XB_XGEN(b.x)], 1u);
.LBB0_1067:
	s_or_b64 exec, exec, s[6:7]
	s_and_saveexec_b64 s[4:5], s[8:9]
	s_cbranch_execz .LBB0_1069
	v_mov_b32_e32 v0, 1
	global_atomic_add v[2:3], v0, off
	buffer_inv sc1
.LBB0_1069:
	s_or_b64 exec, exec, s[4:5]
	s_mov_b64 s[4:5], exec
	v_mbcnt_lo_u32_b32 v0, s4, 0
	v_mbcnt_hi_u32_b32 v0, s5, v0
	v_cmp_eq_u32_e32 vcc, 0, v0
	s_and_saveexec_b64 s[6:7], vcc
	s_cbranch_execnz .LBB0_1070
	s_getpc_b64 s[98:99]
